# counted waits: all 288 transpose LDS read-backs hoisted (21 segments) and LayerNorm gain/bias loads hoisted with counted vmcnt (4 phases)
# baseline (speedup 1.0000x reference)
; __device__ __forceinline__ unsigned cvt_pk_bf16(float lo, float hi) { unsigned r; asm volatile("v_cvt_pk_bf16_f32 %0, %1, %2" : "=v"(r) : "v"(lo), "v"(hi)); return r; }
; #define LAS __attribute__((address_space(3)))
; __device__ __forceinline__ void map_col(int kind, int n, int& drow, float& sc) {
;     ...
;     case MAP_W1:
;         if (n < 1024) sc = 0.08838834764831845f * LOG2E;
;         else if (n >= 3072 && n < 5120) { const int d = n & 127; drow = (n & ~127) + (d < 64 ? 2 * d : 2 * (d - 64) + 1); if (n < 4096) sc = 0.08838834764831845f * LOG2E; }
; __device__ __forceinline__ void transpose_item(const float* W, int K, int N, bf16_t* WT, const float* kscale, int kind, LAS float* scr, int item, int lane) {
;     ...
;     for (int j = 0; j < 4; ++j) {
;         const int n = (lane >> 3) + 8 * j; const LAS float* s = scr + (8 * c) * 33 + n;
;         int drow; float sc; map_col(kind, n0 + n, drow, sc);
;         u32x4 ov; ov.x = cvt_pk_bf16(s[0 * 33] * sc, s[1 * 33] * sc); ov.y = cvt_pk_bf16(s[2 * 33] * sc, s[3 * 33] * sc); ov.z = cvt_pk_bf16(s[4 * 33] * sc, s[5 * 33] * sc); ov.w = cvt_pk_bf16(s[6 * 33] * sc, s[7 * 33] * sc);
;         *(u32x4*)(WT + (size_t)drow * K + k0 + 8 * c) = ov;
.LBB0_75:
	s_or_b64 exec, exec, s[4:5]
	ds_read2_b32 v[100:101], v15 offset0:24 offset1:57
	ds_read2_b32 v[102:103], v15 offset0:90 offset1:123
	ds_read2_b32 v[104:105], v15 offset0:156 offset1:189
	ds_read2_b32 v[106:107], v15 offset0:222 offset1:255
	s_add_i32 s41, s41, s10
	s_add_i32 s18, s18, s19
	s_cmpk_lt_i32 s41, 0x1800
	s_waitcnt lgkmcnt(3)
	v_mul_f32_e32 v11, v34, v100
	s_waitcnt lgkmcnt(3)
	v_mul_f32_e32 v12, v34, v101
	v_cvt_pk_bf16_f32 v36, v11, v12
	s_waitcnt lgkmcnt(2)
	v_mul_f32_e32 v11, v34, v102
	s_waitcnt lgkmcnt(2)
	v_mul_f32_e32 v12, v34, v103
	v_cvt_pk_bf16_f32 v37, v11, v12
	v_ashrrev_i32_e32 v11, 31, v10
	v_lshlrev_b64 v[10:11], 12, v[10:11]
	v_lshl_add_u64 v[8:9], v[8:9], 0, v[10:11]
	s_waitcnt lgkmcnt(1)
	v_mul_f32_e32 v12, v34, v104
	s_waitcnt lgkmcnt(1)
	v_mul_f32_e32 v13, v34, v105
	v_cvt_pk_bf16_f32 v38, v12, v13
	s_waitcnt lgkmcnt(0)
	v_mul_f32_e32 v10, v34, v106
	s_waitcnt lgkmcnt(0)
	v_mul_f32_e32 v11, v34, v107
	v_cvt_pk_bf16_f32 v39, v10, v11
	global_store_dwordx4 v[8:9], v[36:39], off
	s_waitcnt lgkmcnt(0)
	s_cbranch_scc0 .LBB0_91

; __device__ __forceinline__ unsigned cvt_pk_bf16(float lo, float hi) { unsigned r; asm volatile("v_cvt_pk_bf16_f32 %0, %1, %2" : "=v"(r) : "v"(lo), "v"(hi)); return r; }
; #define LAS __attribute__((address_space(3)))
; __device__ __forceinline__ void map_col(int kind, int n, int& drow, float& sc) {
;     ...
;     case MAP_W1:
;         if (n < 1024) sc = 0.08838834764831845f * LOG2E;
;         else if (n >= 3072 && n < 5120) { const int d = n & 127; drow = (n & ~127) + (d < 64 ? 2 * d : 2 * (d - 64) + 1); if (n < 4096) sc = 0.08838834764831845f * LOG2E; }
; __device__ __forceinline__ void transpose_item(const float* W, int K, int N, bf16_t* WT, const float* kscale, int kind, LAS float* scr, int item, int lane) {
;     ...
;     for (int j = 0; j < 4; ++j) {
;         const int n = (lane >> 3) + 8 * j; const LAS float* s = scr + (8 * c) * 33 + n;
;         int drow; float sc; map_col(kind, n0 + n, drow, sc);
;         u32x4 ov; ov.x = cvt_pk_bf16(s[0 * 33] * sc, s[1 * 33] * sc); ov.y = cvt_pk_bf16(s[2 * 33] * sc, s[3 * 33] * sc); ov.z = cvt_pk_bf16(s[4 * 33] * sc, s[5 * 33] * sc); ov.w = cvt_pk_bf16(s[6 * 33] * sc, s[7 * 33] * sc);
;         *(u32x4*)(WT + (size_t)drow * K + k0 + 8 * c) = ov;
.LBB0_80:
	s_or_b64 exec, exec, s[6:7]
	ds_read2_b32 v[100:101], v15 offset1:33
	ds_read2_b32 v[102:103], v15 offset0:66 offset1:99
	ds_read2_b32 v[104:105], v15 offset0:132 offset1:165
	ds_read2_b32 v[106:107], v15 offset0:198 offset1:231
	s_ashr_i32 s5, s4, 31
	v_ashrrev_i32_e32 v13, 31, v12
	v_lshlrev_b64 v[12:13], 12, v[12:13]
	v_add_u32_e32 v10, 8, v33
	s_waitcnt lgkmcnt(3)
	v_mul_f32_e32 v8, v11, v100
	s_waitcnt lgkmcnt(3)
	v_mul_f32_e32 v9, v11, v101
	v_cvt_pk_bf16_f32 v34, v8, v9
	v_cmp_lt_i32_e32 vcc, s38, v10
	s_waitcnt lgkmcnt(2)
	v_mul_f32_e32 v8, v11, v102
	s_waitcnt lgkmcnt(2)
	v_mul_f32_e32 v9, v11, v103
	v_cvt_pk_bf16_f32 v35, v8, v9
	s_waitcnt lgkmcnt(1)
	v_mul_f32_e32 v8, v11, v104
	s_waitcnt lgkmcnt(1)
	v_mul_f32_e32 v9, v11, v105
	v_cvt_pk_bf16_f32 v36, v8, v9
	v_lshl_add_u64 v[8:9], s[4:5], 1, v[4:5]
	v_lshl_add_u64 v[12:13], v[8:9], 0, v[12:13]
	s_waitcnt lgkmcnt(0)
	v_mul_f32_e32 v37, v11, v106
	s_waitcnt lgkmcnt(0)
	v_mul_f32_e32 v11, v11, v107
	v_cvt_pk_bf16_f32 v37, v37, v11
	global_store_dwordx4 v[12:13], v[34:37], off
	v_mov_b32_e32 v13, 0x3e0293ee
	s_and_saveexec_b64 s[4:5], vcc
	s_cbranch_execz .LBB0_84
	v_add_u32_e32 v11, 0xfffff408, v33
	v_cmp_gt_u32_e32 vcc, s39, v11
	v_mov_b32_e32 v13, 1.0
	s_and_saveexec_b64 s[6:7], vcc
	s_cbranch_execz .LBB0_83
	v_and_b32_e32 v11, 0x7f, v10
	v_lshlrev_b32_e32 v13, 1, v11
	v_add_u32_e32 v34, 0xffffff81, v13
	v_cmp_gt_u32_e32 vcc, 64, v11
	v_and_b32_e32 v12, 0x1f80, v10
	s_nop 0
	v_cndmask_b32_e32 v11, v34, v13, vcc
	v_add_u32_e32 v11, v11, v12
	v_cmp_gt_u32_e32 vcc, s40, v10
	v_mov_b32_e32 v10, v11
	s_nop 0
	v_cndmask_b32_e32 v13, 1.0, v32, vcc

; __device__ __forceinline__ unsigned cvt_pk_bf16(float lo, float hi) { unsigned r; asm volatile("v_cvt_pk_bf16_f32 %0, %1, %2" : "=v"(r) : "v"(lo), "v"(hi)); return r; }
; #define LAS __attribute__((address_space(3)))
; __device__ __forceinline__ void map_col(int kind, int n, int& drow, float& sc) {
;     ...
;     case MAP_W1:
;         if (n < 1024) sc = 0.08838834764831845f * LOG2E;
;         else if (n >= 3072 && n < 5120) { const int d = n & 127; drow = (n & ~127) + (d < 64 ? 2 * d : 2 * (d - 64) + 1); if (n < 4096) sc = 0.08838834764831845f * LOG2E; }
; __device__ __forceinline__ void transpose_item(const float* W, int K, int N, bf16_t* WT, const float* kscale, int kind, LAS float* scr, int item, int lane) {
;     ...
;     for (int j = 0; j < 4; ++j) {
;         const int n = (lane >> 3) + 8 * j; const LAS float* s = scr + (8 * c) * 33 + n;
;         int drow; float sc; map_col(kind, n0 + n, drow, sc);
;         u32x4 ov; ov.x = cvt_pk_bf16(s[0 * 33] * sc, s[1 * 33] * sc); ov.y = cvt_pk_bf16(s[2 * 33] * sc, s[3 * 33] * sc); ov.z = cvt_pk_bf16(s[4 * 33] * sc, s[5 * 33] * sc); ov.w = cvt_pk_bf16(s[6 * 33] * sc, s[7 * 33] * sc);
;         *(u32x4*)(WT + (size_t)drow * K + k0 + 8 * c) = ov;
.LBB0_84:
	s_or_b64 exec, exec, s[4:5]
	ds_read2_b32 v[100:101], v15 offset0:8 offset1:41
	ds_read2_b32 v[102:103], v15 offset0:74 offset1:107
	ds_read2_b32 v[104:105], v15 offset0:140 offset1:173
	ds_read2_b32 v[106:107], v15 offset0:206 offset1:239
	s_waitcnt lgkmcnt(3)
	v_mul_f32_e32 v11, v13, v100
	s_waitcnt lgkmcnt(3)
	v_mul_f32_e32 v12, v13, v101
	v_cvt_pk_bf16_f32 v36, v11, v12
	s_waitcnt lgkmcnt(2)
	v_mul_f32_e32 v11, v13, v102
	s_waitcnt lgkmcnt(2)
	v_mul_f32_e32 v12, v13, v103
	v_cvt_pk_bf16_f32 v37, v11, v12
	v_ashrrev_i32_e32 v11, 31, v10
	v_lshlrev_b64 v[10:11], 12, v[10:11]
	v_add_u32_e32 v12, 16, v33
	v_lshl_add_u64 v[10:11], v[8:9], 0, v[10:11]
	s_waitcnt lgkmcnt(1)
	v_mul_f32_e32 v34, v13, v104
	s_waitcnt lgkmcnt(1)
	v_mul_f32_e32 v35, v13, v105
	v_cvt_pk_bf16_f32 v38, v34, v35
	v_mov_b32_e32 v34, 0x3e0293ee
	v_cmp_lt_i32_e32 vcc, s38, v12
	s_waitcnt lgkmcnt(0)
	v_mul_f32_e32 v35, v13, v106
	s_waitcnt lgkmcnt(0)
	v_mul_f32_e32 v13, v13, v107
	v_cvt_pk_bf16_f32 v39, v35, v13
	global_store_dwordx4 v[10:11], v[36:39], off
	v_mov_b32_e32 v11, 0x3e0293ee
	s_and_saveexec_b64 s[4:5], vcc
	s_cbranch_execz .LBB0_88
	v_add_u32_e32 v10, 0xfffff410, v33
	v_cmp_gt_u32_e32 vcc, s39, v10
	v_mov_b32_e32 v11, 1.0
	s_and_saveexec_b64 s[6:7], vcc
	s_cbranch_execz .LBB0_87
	v_and_b32_e32 v10, 0x7f, v12
	v_lshlrev_b32_e32 v13, 1, v10
	v_add_u32_e32 v35, 0xffffff81, v13
	v_cmp_gt_u32_e32 vcc, 64, v10
	v_and_b32_e32 v11, 0x1f80, v12
	s_nop 0
	v_cndmask_b32_e32 v10, v35, v13, vcc
	v_add_u32_e32 v10, v10, v11
	v_cmp_gt_u32_e32 vcc, s40, v12
	v_mov_b32_e32 v12, v10
	s_nop 0
	v_cndmask_b32_e32 v11, 1.0, v32, vcc

; __device__ __forceinline__ unsigned cvt_pk_bf16(float lo, float hi) { unsigned r; asm volatile("v_cvt_pk_bf16_f32 %0, %1, %2" : "=v"(r) : "v"(lo), "v"(hi)); return r; }
; #define LAS __attribute__((address_space(3)))
; __device__ __forceinline__ void map_col(int kind, int n, int& drow, float& sc) {
;     ...
;     case MAP_W1:
;         if (n < 1024) sc = 0.08838834764831845f * LOG2E;
;         else if (n >= 3072 && n < 5120) { const int d = n & 127; drow = (n & ~127) + (d < 64 ? 2 * d : 2 * (d - 64) + 1); if (n < 4096) sc = 0.08838834764831845f * LOG2E; }
; __device__ __forceinline__ void transpose_item(const float* W, int K, int N, bf16_t* WT, const float* kscale, int kind, LAS float* scr, int item, int lane) {
;     ...
;     for (int j = 0; j < 4; ++j) {
;         const int n = (lane >> 3) + 8 * j; const LAS float* s = scr + (8 * c) * 33 + n;
;         int drow; float sc; map_col(kind, n0 + n, drow, sc);
;         u32x4 ov; ov.x = cvt_pk_bf16(s[0 * 33] * sc, s[1 * 33] * sc); ov.y = cvt_pk_bf16(s[2 * 33] * sc, s[3 * 33] * sc); ov.z = cvt_pk_bf16(s[4 * 33] * sc, s[5 * 33] * sc); ov.w = cvt_pk_bf16(s[6 * 33] * sc, s[7 * 33] * sc);
;         *(u32x4*)(WT + (size_t)drow * K + k0 + 8 * c) = ov;
.LBB0_88:
	s_or_b64 exec, exec, s[4:5]
	ds_read2_b32 v[100:101], v15 offset0:16 offset1:49
	ds_read2_b32 v[102:103], v15 offset0:82 offset1:115
	ds_read2_b32 v[104:105], v15 offset0:148 offset1:181
	ds_read2_b32 v[106:107], v15 offset0:214 offset1:247
	s_waitcnt lgkmcnt(3)
	v_mul_f32_e32 v10, v11, v100
	s_waitcnt lgkmcnt(3)
	v_mul_f32_e32 v13, v11, v101
	v_cvt_pk_bf16_f32 v36, v10, v13
	s_waitcnt lgkmcnt(2)
	v_mul_f32_e32 v10, v11, v102
	s_waitcnt lgkmcnt(2)
	v_mul_f32_e32 v13, v11, v103
	v_cvt_pk_bf16_f32 v37, v10, v13
	s_waitcnt lgkmcnt(1)
	v_mul_f32_e32 v10, v11, v104
	s_waitcnt lgkmcnt(1)
	v_mul_f32_e32 v13, v11, v105
	v_cvt_pk_bf16_f32 v38, v10, v13
	v_ashrrev_i32_e32 v13, 31, v12
	v_add_u32_e32 v10, 24, v33
	v_lshlrev_b64 v[12:13], 12, v[12:13]
	v_lshl_add_u64 v[12:13], v[8:9], 0, v[12:13]
	v_cmp_lt_i32_e32 vcc, s38, v10
	s_waitcnt lgkmcnt(0)
	v_mul_f32_e32 v35, v11, v106
	s_waitcnt lgkmcnt(0)
	v_mul_f32_e32 v11, v11, v107
	v_cvt_pk_bf16_f32 v39, v35, v11
	global_store_dwordx4 v[12:13], v[36:39], off
	s_and_saveexec_b64 s[4:5], vcc
	s_cbranch_execz .LBB0_75
	v_add_u32_e32 v11, 0xfffff418, v33
	v_cmp_gt_u32_e32 vcc, s39, v11
	v_mov_b32_e32 v34, 1.0
	s_and_saveexec_b64 s[6:7], vcc
	s_cbranch_execz .LBB0_74
	v_and_b32_e32 v11, 0x7f, v10
	v_lshlrev_b32_e32 v13, 1, v11
	v_add_u32_e32 v33, 0xffffff81, v13
	v_cmp_gt_u32_e32 vcc, 64, v11
	v_and_b32_e32 v12, 0x1f80, v10
	s_nop 0
	v_cndmask_b32_e32 v11, v33, v13, vcc
	v_add_u32_e32 v11, v11, v12
	v_cmp_gt_u32_e32 vcc, s40, v10
	v_mov_b32_e32 v10, v11
	s_nop 0
	v_cndmask_b32_e32 v34, 1.0, v32, vcc
	s_branch .LBB0_74

; __device__ __forceinline__ unsigned cvt_pk_bf16(float lo, float hi) { unsigned r; asm volatile("v_cvt_pk_bf16_f32 %0, %1, %2" : "=v"(r) : "v"(lo), "v"(hi)); return r; }
; __device__ __forceinline__ void ln_row(const float* in, float* out, bf16_t* outb, float* stat, const float* g, const float* bta, int lane) {
;     ...
;     for (int j = 0; j < 8; ++j) {
;         const f32x4 gg = *(const f32x4*)(g + 256 * j + 4 * lane), bb = *(const f32x4*)(bta + 256 * j + 4 * lane);
;         const f32x4 y = v[j] * rstd * gg + bb;
;         if (out) *(f32x4*)(out + 256 * j + 4 * lane) = y;
;         if (outb) { u32x2 w; w.x = cvt_pk_bf16(y[0], y[1]); w.y = cvt_pk_bf16(y[2], y[3]); *(u32x2*)(outb + 256 * j + 4 * lane) = w; }
;     }
.LBB0_532:
	s_or_b64 exec, exec, s[6:7]
	global_load_dwordx4 v[100:103], v[34:35], off
	global_load_dwordx4 v[104:107], v[36:37], off
	global_load_dwordx4 v[108:111], v[34:35], off offset:1024
	global_load_dwordx4 v[112:115], v[36:37], off offset:1024
	global_load_dwordx4 v[116:119], v[34:35], off offset:2048
	global_load_dwordx4 v[120:123], v[36:37], off offset:2048
	global_load_dwordx4 v[124:127], v[34:35], off offset:3072
	global_load_dwordx4 v[128:131], v[36:37], off offset:3072
	global_load_dwordx4 v[132:135], v[38:39], off
	global_load_dwordx4 v[136:139], v[40:41], off
	global_load_dwordx4 v[140:143], v[42:43], off
	global_load_dwordx4 v[144:147], v[44:45], off
	global_load_dwordx4 v[148:151], v[46:47], off
	global_load_dwordx4 v[152:155], v[48:49], off
	global_load_dwordx4 v[156:159], v[50:51], off
	global_load_dwordx4 v[160:163], v[52:53], off
	v_lshl_add_u64 v[74:75], s[14:15], 0, v[54:55]
	v_pk_mul_f32 v[28:29], v[28:29], v[32:33] op_sel_hi:[1,0]
	v_add_co_u32_e32 v74, vcc, s21, v74
	v_pk_mul_f32 v[30:31], v[30:31], v[32:33] op_sel_hi:[1,0]
	s_nop 0
	v_addc_co_u32_e32 v75, vcc, 0, v75, vcc
	v_pk_mul_f32 v[24:25], v[24:25], v[32:33] op_sel_hi:[1,0]
	v_pk_mul_f32 v[26:27], v[26:27], v[32:33] op_sel_hi:[1,0]
	v_pk_mul_f32 v[20:21], v[20:21], v[32:33] op_sel_hi:[1,0]
	v_pk_mul_f32 v[22:23], v[22:23], v[32:33] op_sel_hi:[1,0]
	v_pk_mul_f32 v[16:17], v[16:17], v[32:33] op_sel_hi:[1,0]
	v_pk_mul_f32 v[18:19], v[18:19], v[32:33] op_sel_hi:[1,0]
	v_pk_mul_f32 v[12:13], v[12:13], v[32:33] op_sel_hi:[1,0]
	v_pk_mul_f32 v[14:15], v[14:15], v[32:33] op_sel_hi:[1,0]
	v_pk_mul_f32 v[8:9], v[8:9], v[32:33] op_sel_hi:[1,0]
	v_pk_mul_f32 v[10:11], v[10:11], v[32:33] op_sel_hi:[1,0]
	v_pk_mul_f32 v[4:5], v[4:5], v[32:33] op_sel_hi:[1,0]
	v_pk_mul_f32 v[6:7], v[6:7], v[32:33] op_sel_hi:[1,0]
	s_add_i32 s18, s18, s20
	s_add_u32 s22, s22, s8
	v_pk_mul_f32 v[0:1], v[0:1], v[32:33] op_sel_hi:[1,0]
	s_addc_u32 s23, s23, s9
	v_pk_mul_f32 v[2:3], v[2:3], v[32:33] op_sel_hi:[1,0]
	v_lshl_add_u64 v[54:55], v[54:55], 0, s[10:11]
	s_cmpk_lt_i32 s18, 0x4000
	v_lshl_add_u64 v[56:57], v[56:57], 0, s[12:13]
	s_waitcnt vmcnt(14)
	v_pk_fma_f32 v[28:29], v[28:29], v[100:101], v[104:105]
	s_waitcnt vmcnt(14)
	v_pk_fma_f32 v[30:31], v[30:31], v[102:103], v[106:107]
	v_cvt_pk_bf16_f32 v28, v28, v29
	s_nop 0
	v_cvt_pk_bf16_f32 v29, v30, v31
	global_store_dwordx2 v[74:75], v[28:29], off
	s_nop 0
	s_waitcnt vmcnt(13)
	v_pk_fma_f32 v[24:25], v[24:25], v[108:109], v[112:113]
	s_waitcnt vmcnt(13)
	v_pk_fma_f32 v[26:27], v[26:27], v[110:111], v[114:115]
	v_cvt_pk_bf16_f32 v24, v24, v25
	s_nop 0
	v_cvt_pk_bf16_f32 v25, v26, v27
	global_store_dwordx2 v[74:75], v[24:25], off offset:512
	s_nop 0
	s_waitcnt vmcnt(12)
	v_pk_fma_f32 v[20:21], v[20:21], v[116:117], v[120:121]
	s_waitcnt vmcnt(12)
	v_pk_fma_f32 v[22:23], v[22:23], v[118:119], v[122:123]
	v_cvt_pk_bf16_f32 v20, v20, v21
	s_nop 0
	v_cvt_pk_bf16_f32 v21, v22, v23
	global_store_dwordx2 v[74:75], v[20:21], off offset:1024
	s_nop 0
	s_waitcnt vmcnt(11)
	v_pk_fma_f32 v[16:17], v[16:17], v[124:125], v[128:129]
	s_waitcnt vmcnt(11)
	v_pk_fma_f32 v[18:19], v[18:19], v[126:127], v[130:131]
	v_cvt_pk_bf16_f32 v16, v16, v17
	s_nop 0
	v_cvt_pk_bf16_f32 v17, v18, v19
	global_store_dwordx2 v[74:75], v[16:17], off offset:1536
	s_nop 0
	s_waitcnt vmcnt(10)
	v_pk_fma_f32 v[12:13], v[12:13], v[132:133], v[136:137]
	s_waitcnt vmcnt(10)
	v_pk_fma_f32 v[14:15], v[14:15], v[134:135], v[138:139]
	v_cvt_pk_bf16_f32 v12, v12, v13
	s_nop 0
	v_cvt_pk_bf16_f32 v13, v14, v15
	global_store_dwordx2 v[74:75], v[12:13], off offset:2048
	s_nop 0
	s_waitcnt vmcnt(9)
	v_pk_fma_f32 v[8:9], v[8:9], v[140:141], v[144:145]
	s_waitcnt vmcnt(9)
	v_pk_fma_f32 v[10:11], v[10:11], v[142:143], v[146:147]
	v_cvt_pk_bf16_f32 v8, v8, v9
	s_nop 0
	v_cvt_pk_bf16_f32 v9, v10, v11
	global_store_dwordx2 v[74:75], v[8:9], off offset:2560
	s_nop 0
	s_waitcnt vmcnt(8)
	v_pk_fma_f32 v[4:5], v[4:5], v[148:149], v[152:153]
	s_waitcnt vmcnt(8)
	v_pk_fma_f32 v[6:7], v[6:7], v[150:151], v[154:155]
	v_cvt_pk_bf16_f32 v4, v4, v5
	s_nop 0
	v_cvt_pk_bf16_f32 v5, v6, v7
	global_store_dwordx2 v[74:75], v[4:5], off offset:3072
	s_nop 0
	s_waitcnt vmcnt(7)
	v_pk_fma_f32 v[0:1], v[0:1], v[156:157], v[160:161]
	s_waitcnt vmcnt(7)
	v_pk_fma_f32 v[2:3], v[2:3], v[158:159], v[162:163]
	v_cvt_pk_bf16_f32 v0, v0, v1
	s_nop 0
	v_cvt_pk_bf16_f32 v1, v2, v3
	global_store_dwordx2 v[74:75], v[0:1], off offset:3584
	s_cbranch_scc0 .LBB0_535

; __device__ __forceinline__ unsigned cvt_pk_bf16(float lo, float hi) { unsigned r; asm volatile("v_cvt_pk_bf16_f32 %0, %1, %2" : "=v"(r) : "v"(lo), "v"(hi)); return r; }
; __device__ __forceinline__ void ln_row(const float* in, float* out, bf16_t* outb, float* stat, const float* g, const float* bta, int lane) {
;     ...
;     for (int j = 0; j < 8; ++j) {
;         const f32x4 gg = *(const f32x4*)(g + 256 * j + 4 * lane), bb = *(const f32x4*)(bta + 256 * j + 4 * lane);
;         const f32x4 y = v[j] * rstd * gg + bb;
;         if (out) *(f32x4*)(out + 256 * j + 4 * lane) = y;
;         if (outb) { u32x2 w; w.x = cvt_pk_bf16(y[0], y[1]); w.y = cvt_pk_bf16(y[2], y[3]); *(u32x2*)(outb + 256 * j + 4 * lane) = w; }
;     }
.LBB0_752:
	s_or_b64 exec, exec, s[6:7]
	global_load_dwordx4 v[100:103], v[34:35], off
	global_load_dwordx4 v[104:107], v[36:37], off
	global_load_dwordx4 v[108:111], v[34:35], off offset:1024
	global_load_dwordx4 v[112:115], v[36:37], off offset:1024
	global_load_dwordx4 v[116:119], v[34:35], off offset:2048
	global_load_dwordx4 v[120:123], v[36:37], off offset:2048
	global_load_dwordx4 v[124:127], v[34:35], off offset:3072
	global_load_dwordx4 v[128:131], v[36:37], off offset:3072
	global_load_dwordx4 v[132:135], v[38:39], off
	global_load_dwordx4 v[136:139], v[40:41], off
	global_load_dwordx4 v[140:143], v[42:43], off
	global_load_dwordx4 v[144:147], v[44:45], off
	global_load_dwordx4 v[148:151], v[46:47], off
	global_load_dwordx4 v[152:155], v[48:49], off
	global_load_dwordx4 v[156:159], v[50:51], off
	global_load_dwordx4 v[160:163], v[52:53], off
	v_lshl_add_u64 v[76:77], s[10:11], 0, v[54:55]
	v_pk_mul_f32 v[28:29], v[28:29], v[32:33] op_sel_hi:[1,0]
	v_add_co_u32_e32 v76, vcc, s17, v76
	v_pk_mul_f32 v[30:31], v[30:31], v[32:33] op_sel_hi:[1,0]
	s_nop 0
	v_addc_co_u32_e32 v77, vcc, 0, v77, vcc
	v_pk_mul_f32 v[24:25], v[24:25], v[32:33] op_sel_hi:[1,0]
	v_pk_mul_f32 v[26:27], v[26:27], v[32:33] op_sel_hi:[1,0]
	v_pk_mul_f32 v[20:21], v[20:21], v[32:33] op_sel_hi:[1,0]
	v_pk_mul_f32 v[22:23], v[22:23], v[32:33] op_sel_hi:[1,0]
	v_pk_mul_f32 v[16:17], v[16:17], v[32:33] op_sel_hi:[1,0]
	v_pk_mul_f32 v[18:19], v[18:19], v[32:33] op_sel_hi:[1,0]
	v_pk_mul_f32 v[12:13], v[12:13], v[32:33] op_sel_hi:[1,0]
	v_pk_mul_f32 v[14:15], v[14:15], v[32:33] op_sel_hi:[1,0]
	v_pk_mul_f32 v[8:9], v[8:9], v[32:33] op_sel_hi:[1,0]
	v_pk_mul_f32 v[10:11], v[10:11], v[32:33] op_sel_hi:[1,0]
	v_pk_mul_f32 v[4:5], v[4:5], v[32:33] op_sel_hi:[1,0]
	v_pk_mul_f32 v[6:7], v[6:7], v[32:33] op_sel_hi:[1,0]
	s_add_i32 s26, s26, s12
	s_add_u32 s24, s24, s20
	v_pk_mul_f32 v[0:1], v[0:1], v[32:33] op_sel_hi:[1,0]
	s_addc_u32 s25, s25, s21
	v_pk_mul_f32 v[2:3], v[2:3], v[32:33] op_sel_hi:[1,0]
	v_lshl_add_u64 v[54:55], v[54:55], 0, s[22:23]
	s_cmpk_gt_i32 s26, 0x3fff
	v_lshl_add_u64 v[56:57], v[56:57], 0, s[8:9]
	s_waitcnt vmcnt(14)
	v_pk_fma_f32 v[28:29], v[28:29], v[100:101], v[104:105]
	s_waitcnt vmcnt(14)
	v_pk_fma_f32 v[30:31], v[30:31], v[102:103], v[106:107]
	v_cvt_pk_bf16_f32 v28, v28, v29
	s_nop 0
	v_cvt_pk_bf16_f32 v29, v30, v31
	global_store_dwordx2 v[76:77], v[28:29], off
	s_nop 0
	s_waitcnt vmcnt(13)
	v_pk_fma_f32 v[24:25], v[24:25], v[108:109], v[112:113]
	s_waitcnt vmcnt(13)
	v_pk_fma_f32 v[26:27], v[26:27], v[110:111], v[114:115]
	v_cvt_pk_bf16_f32 v24, v24, v25
	s_nop 0
	v_cvt_pk_bf16_f32 v25, v26, v27
	global_store_dwordx2 v[76:77], v[24:25], off offset:512
	s_nop 0
	s_waitcnt vmcnt(12)
	v_pk_fma_f32 v[20:21], v[20:21], v[116:117], v[120:121]
	s_waitcnt vmcnt(12)
	v_pk_fma_f32 v[22:23], v[22:23], v[118:119], v[122:123]
	v_cvt_pk_bf16_f32 v20, v20, v21
	s_nop 0
	v_cvt_pk_bf16_f32 v21, v22, v23
	global_store_dwordx2 v[76:77], v[20:21], off offset:1024
	s_nop 0
	s_waitcnt vmcnt(11)
	v_pk_fma_f32 v[16:17], v[16:17], v[124:125], v[128:129]
	s_waitcnt vmcnt(11)
	v_pk_fma_f32 v[18:19], v[18:19], v[126:127], v[130:131]
	v_cvt_pk_bf16_f32 v16, v16, v17
	s_nop 0
	v_cvt_pk_bf16_f32 v17, v18, v19
	global_store_dwordx2 v[76:77], v[16:17], off offset:1536
	s_nop 0
	s_waitcnt vmcnt(10)
	v_pk_fma_f32 v[12:13], v[12:13], v[132:133], v[136:137]
	s_waitcnt vmcnt(10)
	v_pk_fma_f32 v[14:15], v[14:15], v[134:135], v[138:139]
	v_cvt_pk_bf16_f32 v12, v12, v13
	s_nop 0
	v_cvt_pk_bf16_f32 v13, v14, v15
	global_store_dwordx2 v[76:77], v[12:13], off offset:2048
	s_nop 0
	s_waitcnt vmcnt(9)
	v_pk_fma_f32 v[8:9], v[8:9], v[140:141], v[144:145]
	s_waitcnt vmcnt(9)
	v_pk_fma_f32 v[10:11], v[10:11], v[142:143], v[146:147]
	v_cvt_pk_bf16_f32 v8, v8, v9
	s_nop 0
	v_cvt_pk_bf16_f32 v9, v10, v11
	global_store_dwordx2 v[76:77], v[8:9], off offset:2560
	s_nop 0
	s_waitcnt vmcnt(8)
	v_pk_fma_f32 v[4:5], v[4:5], v[148:149], v[152:153]
	s_waitcnt vmcnt(8)
	v_pk_fma_f32 v[6:7], v[6:7], v[150:151], v[154:155]
	v_cvt_pk_bf16_f32 v4, v4, v5
	s_nop 0
	v_cvt_pk_bf16_f32 v5, v6, v7
	global_store_dwordx2 v[76:77], v[4:5], off offset:3072
	s_nop 0
	s_waitcnt vmcnt(7)
	v_pk_fma_f32 v[0:1], v[0:1], v[156:157], v[160:161]
	s_waitcnt vmcnt(7)
	v_pk_fma_f32 v[2:3], v[2:3], v[158:159], v[162:163]
	v_cvt_pk_bf16_f32 v0, v0, v1
	s_nop 0
	v_cvt_pk_bf16_f32 v1, v2, v3
	global_store_dwordx2 v[76:77], v[0:1], off offset:3584
	s_cbranch_scc1 .LBB0_755

; __device__ __forceinline__ unsigned cvt_pk_bf16(float lo, float hi) { unsigned r; asm volatile("v_cvt_pk_bf16_f32 %0, %1, %2" : "=v"(r) : "v"(lo), "v"(hi)); return r; }
; #define LAS __attribute__((address_space(3)))
; __device__ __forceinline__ void map_col(int kind, int n, int& drow, float& sc) {
;     ...
;     case MAP_WQ: { const int hd = n / 192, d = n - hd * 192; if (d >= 128) { const int e = d - 128; drow = hd * 192 + 128 + (e < 32 ? 2 * e : 2 * (e - 32) + 1); } sc = 0.07216878364870322f * LOG2E; } break;
; __device__ __forceinline__ void transpose_item(const float* W, int K, int N, bf16_t* WT, const float* kscale, int kind, LAS float* scr, int item, int lane) {
;     const int nblk = N / 32, kb = item / nblk, nb = item % nblk, k0 = 64 * kb, n0 = 32 * nb;
;     {
;         const float* src = W + (size_t)(k0 + (lane >> 3)) * N + n0 + (lane & 7) * 4;
;         f32x4 t[8];
; #pragma unroll
;         for (int i = 0; i < 8; ++i) t[i] = *(const f32x4*)(src + (size_t)(8 * i) * N);
; #pragma unroll
;         for (int i = 0; i < 8; ++i) {
;             const int kk = 8 * i + (lane >> 3);
;             f32x4 v = t[i]; if (kscale) v = v * kscale[k0 + kk];
;             LAS float* d = scr + kk * 33 + (lane & 7) * 4;
;             d[0] = v[0]; d[1] = v[1]; d[2] = v[2]; d[3] = v[3];
;         }
;     }
;     asm volatile("s_waitcnt lgkmcnt(0)" ::: "memory");
;     const int c = lane & 7;
; #pragma unroll
;     for (int j = 0; j < 4; ++j) {
;         const int n = (lane >> 3) + 8 * j; const LAS float* s = scr + (8 * c) * 33 + n;
;         int drow; float sc; map_col(kind, n0 + n, drow, sc);
;         u32x4 ov; ov.x = cvt_pk_bf16(s[0 * 33] * sc, s[1 * 33] * sc); ov.y = cvt_pk_bf16(s[2 * 33] * sc, s[3 * 33] * sc); ov.z = cvt_pk_bf16(s[4 * 33] * sc, s[5 * 33] * sc); ov.w = cvt_pk_bf16(s[6 * 33] * sc, s[7 * 33] * sc);
;         *(u32x4*)(WT + (size_t)drow * K + k0 + 8 * c) = ov;
;     }
;     asm volatile("s_waitcnt lgkmcnt(0)" ::: "memory");
; }
;     ...
;                 transpose_matrix(p.in[I_WQUP], 512, 3072, (bf16_t*)(wsw + W1_Q), p.in[I_QNG], MAP_WQ, scr, gw, NGW, lane);
.LBB0_763:
	s_waitcnt vmcnt(2)
	ds_write2_b32 v62, v14, v15 offset1:1
	ds_write2_b32 v63, v12, v13 offset1:1
	ds_write2_b32 v64, v8, v9 offset1:1
	ds_write2_b32 v65, v10, v11 offset1:1
	s_waitcnt lgkmcnt(0)
	s_waitcnt vmcnt(1)
	ds_read2_b32 v[100:101], v50 offset1:33
	ds_read2_b32 v[102:103], v50 offset0:66 offset1:99
	ds_read2_b32 v[104:105], v50 offset0:132 offset1:165
	ds_read2_b32 v[106:107], v50 offset0:198 offset1:231
	ds_read2_b32 v[108:109], v50 offset0:8 offset1:41
	ds_read2_b32 v[110:111], v50 offset0:74 offset1:107
	ds_read2_b32 v[112:113], v50 offset0:140 offset1:173
	ds_read2_b32 v[114:115], v50 offset0:206 offset1:239
	ds_read2_b32 v[116:117], v50 offset0:16 offset1:49
	ds_read2_b32 v[118:119], v50 offset0:82 offset1:115
	ds_read2_b32 v[120:121], v50 offset0:148 offset1:181
	ds_read2_b32 v[122:123], v50 offset0:214 offset1:247
	ds_read2_b32 v[124:125], v50 offset0:24 offset1:57
	ds_read2_b32 v[126:127], v50 offset0:90 offset1:123
	ds_read2_b32 v[128:129], v50 offset0:156 offset1:189
	ds_read2_b32 v[130:131], v50 offset0:222 offset1:255
	v_add_u32_e32 v10, s13, v48
	v_add_u32_e32 v11, s47, v10
	s_waitcnt vmcnt(0)
	v_mul_hi_i32 v6, v11, s22
	v_lshrrev_b32_e32 v7, 31, v6
	s_waitcnt lgkmcnt(15)
	v_mul_f32_e32 v0, 0x3dd53b94, v100
	s_waitcnt lgkmcnt(15)
	v_mul_f32_e32 v1, 0x3dd53b94, v101
	v_cvt_pk_bf16_f32 v0, v0, v1
	v_lshrrev_b32_e32 v1, 5, v6
	v_add_u32_e32 v1, v1, v7
	v_mul_lo_u32 v1, v1, s38
	v_sub_u32_e32 v8, v11, v1
	s_waitcnt lgkmcnt(14)
	v_mul_f32_e32 v1, 0x3dd53b94, v102
	s_waitcnt lgkmcnt(14)
	v_mul_f32_e32 v2, 0x3dd53b94, v103
	v_cvt_pk_bf16_f32 v1, v1, v2
	v_cmp_gt_u32_e32 vcc, s40, v8
	s_mulk_i32 s46, 0xc00
	s_ashr_i32 s9, s8, 31
	v_cndmask_b32_e32 v6, v66, v67, vcc
	s_waitcnt lgkmcnt(13)
	v_mul_f32_e32 v2, 0x3dd53b94, v104
	v_add_u32_e32 v9, v6, v8
	s_waitcnt lgkmcnt(13)
	v_mul_f32_e32 v3, 0x3dd53b94, v105
	v_cvt_pk_bf16_f32 v2, v2, v3
	v_subrev_u32_e32 v3, s46, v9
	v_add3_u32 v3, v10, v3, s41
	v_cmp_lt_i32_e32 vcc, s39, v8
	v_lshl_add_u64 v[4:5], s[8:9], 1, v[38:39]
	v_add_u32_e32 v12, 8, v11
	v_cndmask_b32_e32 v8, v11, v3, vcc
	s_waitcnt lgkmcnt(12)
	v_mul_f32_e32 v3, 0x3dd53b94, v106
	s_waitcnt lgkmcnt(12)
	v_mul_f32_e32 v6, 0x3dd53b94, v107
	v_ashrrev_i32_e32 v9, 31, v8
	v_cvt_pk_bf16_f32 v3, v3, v6
	v_lshlrev_b64 v[6:7], 10, v[8:9]
	v_lshl_add_u64 v[6:7], v[4:5], 0, v[6:7]
	global_store_dwordx4 v[6:7], v[0:3], off
	s_add_i32 s45, s45, s12
	s_add_i32 s13, s13, s17
	s_waitcnt lgkmcnt(11)
	v_mul_f32_e32 v0, 0x3dd53b94, v108
	s_waitcnt lgkmcnt(11)
	v_mul_f32_e32 v2, 0x3dd53b94, v109
	v_cvt_pk_bf16_f32 v0, v0, v2
	v_mul_hi_i32 v1, v12, s22
	v_lshrrev_b32_e32 v6, 31, v1
	v_lshrrev_b32_e32 v1, 5, v1
	v_add_u32_e32 v1, v1, v6
	v_mul_lo_u32 v6, v1, s38
	s_waitcnt lgkmcnt(10)
	v_mul_f32_e32 v1, 0x3dd53b94, v110
	s_waitcnt lgkmcnt(10)
	v_mul_f32_e32 v2, 0x3dd53b94, v111
	v_cvt_pk_bf16_f32 v1, v1, v2
	v_sub_u32_e32 v8, v12, v6
	v_cmp_gt_u32_e32 vcc, s40, v8
	s_cmpk_lt_i32 s45, 0x300
	s_waitcnt lgkmcnt(9)
	v_mul_f32_e32 v2, 0x3dd53b94, v112
	v_cndmask_b32_e32 v6, v66, v67, vcc
	v_add_u32_e32 v9, v6, v8
	s_waitcnt lgkmcnt(9)
	v_mul_f32_e32 v3, 0x3dd53b94, v113
	v_cvt_pk_bf16_f32 v2, v2, v3
	v_subrev_u32_e32 v3, s46, v9
	v_add3_u32 v3, v10, v3, s42
	v_cmp_lt_i32_e32 vcc, s39, v8
	s_nop 1
	v_cndmask_b32_e32 v8, v12, v3, vcc
	s_waitcnt lgkmcnt(8)
	v_mul_f32_e32 v3, 0x3dd53b94, v114
	s_waitcnt lgkmcnt(8)
	v_mul_f32_e32 v6, 0x3dd53b94, v115
	v_ashrrev_i32_e32 v9, 31, v8
	v_cvt_pk_bf16_f32 v3, v3, v6
	v_lshlrev_b64 v[6:7], 10, v[8:9]
	v_lshl_add_u64 v[6:7], v[4:5], 0, v[6:7]
	global_store_dwordx4 v[6:7], v[0:3], off
	v_add_u32_e32 v12, 16, v11
	v_add_u32_e32 v11, 24, v11
	s_waitcnt lgkmcnt(7)
	v_mul_f32_e32 v0, 0x3dd53b94, v116
	s_waitcnt lgkmcnt(7)
	v_mul_f32_e32 v2, 0x3dd53b94, v117
	v_cvt_pk_bf16_f32 v0, v0, v2
	v_mul_hi_i32 v1, v12, s22
	v_lshrrev_b32_e32 v6, 31, v1
	v_lshrrev_b32_e32 v1, 5, v1
	v_add_u32_e32 v1, v1, v6
	v_mul_lo_u32 v6, v1, s38
	s_waitcnt lgkmcnt(6)
	v_mul_f32_e32 v1, 0x3dd53b94, v118
	s_waitcnt lgkmcnt(6)
	v_mul_f32_e32 v2, 0x3dd53b94, v119
	v_cvt_pk_bf16_f32 v1, v1, v2
	v_sub_u32_e32 v8, v12, v6
	v_cmp_gt_u32_e32 vcc, s40, v8
	s_waitcnt lgkmcnt(5)
	v_mul_f32_e32 v2, 0x3dd53b94, v120
	v_cndmask_b32_e32 v6, v66, v67, vcc
	v_add_u32_e32 v9, v6, v8
	s_waitcnt lgkmcnt(5)
	v_mul_f32_e32 v3, 0x3dd53b94, v121
	v_cvt_pk_bf16_f32 v2, v2, v3
	v_subrev_u32_e32 v3, s46, v9
	v_add3_u32 v3, v10, v3, s43
	v_cmp_lt_i32_e32 vcc, s39, v8
	s_nop 1
	v_cndmask_b32_e32 v8, v12, v3, vcc
	s_waitcnt lgkmcnt(4)
	v_mul_f32_e32 v3, 0x3dd53b94, v122
	s_waitcnt lgkmcnt(4)
	v_mul_f32_e32 v6, 0x3dd53b94, v123
	v_ashrrev_i32_e32 v9, 31, v8
	v_cvt_pk_bf16_f32 v3, v3, v6
	v_lshlrev_b64 v[6:7], 10, v[8:9]
	v_lshl_add_u64 v[6:7], v[4:5], 0, v[6:7]
	global_store_dwordx4 v[6:7], v[0:3], off
	s_nop 0
	s_waitcnt lgkmcnt(3)
	v_mul_f32_e32 v0, 0x3dd53b94, v124
	s_waitcnt lgkmcnt(3)
	v_mul_f32_e32 v2, 0x3dd53b94, v125
	v_cvt_pk_bf16_f32 v0, v0, v2
	v_mul_hi_i32 v1, v11, s22
	v_lshrrev_b32_e32 v6, 31, v1
	v_lshrrev_b32_e32 v1, 5, v1
	v_add_u32_e32 v1, v1, v6
	v_mul_lo_u32 v6, v1, s38
	s_waitcnt lgkmcnt(2)
	v_mul_f32_e32 v1, 0x3dd53b94, v126
	s_waitcnt lgkmcnt(2)
	v_mul_f32_e32 v2, 0x3dd53b94, v127
	v_cvt_pk_bf16_f32 v1, v1, v2
	v_sub_u32_e32 v8, v11, v6
	v_cmp_gt_u32_e32 vcc, s40, v8
	s_waitcnt lgkmcnt(1)
	v_mul_f32_e32 v2, 0x3dd53b94, v128
	v_cndmask_b32_e32 v6, v66, v67, vcc
	v_add_u32_e32 v9, v6, v8
	s_waitcnt lgkmcnt(1)
	v_mul_f32_e32 v3, 0x3dd53b94, v129
	v_cvt_pk_bf16_f32 v2, v2, v3
	v_subrev_u32_e32 v3, s46, v9
	v_add3_u32 v3, v10, v3, s44
	v_cmp_lt_i32_e32 vcc, s39, v8
	s_nop 1
	v_cndmask_b32_e32 v8, v11, v3, vcc
	s_waitcnt lgkmcnt(0)
	v_mul_f32_e32 v3, 0x3dd53b94, v130
	s_waitcnt lgkmcnt(0)
	v_mul_f32_e32 v6, 0x3dd53b94, v131
	v_ashrrev_i32_e32 v9, 31, v8
	v_cvt_pk_bf16_f32 v3, v3, v6
	v_lshlrev_b64 v[6:7], 10, v[8:9]
	v_lshl_add_u64 v[4:5], v[4:5], 0, v[6:7]
	global_store_dwordx4 v[4:5], v[0:3], off
	s_waitcnt lgkmcnt(0)
	s_cbranch_scc0 .LBB0_780

; __device__ __forceinline__ unsigned cvt_pk_bf16(float lo, float hi) { unsigned r; asm volatile("v_cvt_pk_bf16_f32 %0, %1, %2" : "=v"(r) : "v"(lo), "v"(hi)); return r; }
; __device__ __forceinline__ void ln_row(const float* in, float* out, bf16_t* outb, float* stat, const float* g, const float* bta, int lane) {
;     ...
;     for (int j = 0; j < 8; ++j) {
;         const f32x4 gg = *(const f32x4*)(g + 256 * j + 4 * lane), bb = *(const f32x4*)(bta + 256 * j + 4 * lane);
;         const f32x4 y = v[j] * rstd * gg + bb;
;         if (out) *(f32x4*)(out + 256 * j + 4 * lane) = y;
;         if (outb) { u32x2 w; w.x = cvt_pk_bf16(y[0], y[1]); w.y = cvt_pk_bf16(y[2], y[3]); *(u32x2*)(outb + 256 * j + 4 * lane) = w; }
;     }
.LBB0_1319:
	s_or_b64 exec, exec, s[6:7]
	global_load_dwordx4 v[100:103], v[34:35], off
	global_load_dwordx4 v[104:107], v[36:37], off
	global_load_dwordx4 v[108:111], v[34:35], off offset:1024
	global_load_dwordx4 v[112:115], v[36:37], off offset:1024
	global_load_dwordx4 v[116:119], v[34:35], off offset:2048
	global_load_dwordx4 v[120:123], v[36:37], off offset:2048
	global_load_dwordx4 v[124:127], v[34:35], off offset:3072
	global_load_dwordx4 v[128:131], v[36:37], off offset:3072
	global_load_dwordx4 v[132:135], v[38:39], off
	global_load_dwordx4 v[136:139], v[40:41], off
	global_load_dwordx4 v[140:143], v[42:43], off
	global_load_dwordx4 v[144:147], v[44:45], off
	global_load_dwordx4 v[148:151], v[46:47], off
	global_load_dwordx4 v[152:155], v[48:49], off
	global_load_dwordx4 v[156:159], v[50:51], off
	global_load_dwordx4 v[160:163], v[52:53], off
	v_lshl_add_u64 v[76:77], s[10:11], 0, v[54:55]
	v_pk_mul_f32 v[28:29], v[28:29], v[32:33] op_sel_hi:[1,0]
	v_add_co_u32_e32 v76, vcc, s21, v76
	v_pk_mul_f32 v[30:31], v[30:31], v[32:33] op_sel_hi:[1,0]
	s_nop 0
	v_addc_co_u32_e32 v77, vcc, 0, v77, vcc
	v_pk_mul_f32 v[24:25], v[24:25], v[32:33] op_sel_hi:[1,0]
	v_pk_mul_f32 v[26:27], v[26:27], v[32:33] op_sel_hi:[1,0]
	v_pk_mul_f32 v[20:21], v[20:21], v[32:33] op_sel_hi:[1,0]
	v_pk_mul_f32 v[22:23], v[22:23], v[32:33] op_sel_hi:[1,0]
	v_pk_mul_f32 v[16:17], v[16:17], v[32:33] op_sel_hi:[1,0]
	v_pk_mul_f32 v[18:19], v[18:19], v[32:33] op_sel_hi:[1,0]
	v_pk_mul_f32 v[12:13], v[12:13], v[32:33] op_sel_hi:[1,0]
	v_pk_mul_f32 v[14:15], v[14:15], v[32:33] op_sel_hi:[1,0]
	v_pk_mul_f32 v[8:9], v[8:9], v[32:33] op_sel_hi:[1,0]
	v_pk_mul_f32 v[10:11], v[10:11], v[32:33] op_sel_hi:[1,0]
	v_pk_mul_f32 v[4:5], v[4:5], v[32:33] op_sel_hi:[1,0]
	v_pk_mul_f32 v[6:7], v[6:7], v[32:33] op_sel_hi:[1,0]
	s_add_i32 s18, s18, s20
	s_add_u32 s12, s12, s22
	v_pk_mul_f32 v[0:1], v[0:1], v[32:33] op_sel_hi:[1,0]
	s_addc_u32 s26, s26, s23
	v_pk_mul_f32 v[2:3], v[2:3], v[32:33] op_sel_hi:[1,0]
	v_lshl_add_u64 v[54:55], v[54:55], 0, s[24:25]
	s_cmpk_gt_i32 s18, 0x3fff
	v_lshl_add_u64 v[56:57], v[56:57], 0, s[8:9]
	s_waitcnt vmcnt(14)
	v_pk_fma_f32 v[28:29], v[28:29], v[100:101], v[104:105]
	s_waitcnt vmcnt(14)
	v_pk_fma_f32 v[30:31], v[30:31], v[102:103], v[106:107]
	v_cvt_pk_bf16_f32 v28, v28, v29
	s_nop 0
	v_cvt_pk_bf16_f32 v29, v30, v31
	global_store_dwordx2 v[76:77], v[28:29], off
	s_nop 0
	s_waitcnt vmcnt(13)
	v_pk_fma_f32 v[24:25], v[24:25], v[108:109], v[112:113]
	s_waitcnt vmcnt(13)
	v_pk_fma_f32 v[26:27], v[26:27], v[110:111], v[114:115]
	v_cvt_pk_bf16_f32 v24, v24, v25
	s_nop 0
	v_cvt_pk_bf16_f32 v25, v26, v27
	global_store_dwordx2 v[76:77], v[24:25], off offset:512
	s_nop 0
	s_waitcnt vmcnt(12)
	v_pk_fma_f32 v[20:21], v[20:21], v[116:117], v[120:121]
	s_waitcnt vmcnt(12)
	v_pk_fma_f32 v[22:23], v[22:23], v[118:119], v[122:123]
	v_cvt_pk_bf16_f32 v20, v20, v21
	s_nop 0
	v_cvt_pk_bf16_f32 v21, v22, v23
	global_store_dwordx2 v[76:77], v[20:21], off offset:1024
	s_nop 0
	s_waitcnt vmcnt(11)
	v_pk_fma_f32 v[16:17], v[16:17], v[124:125], v[128:129]
	s_waitcnt vmcnt(11)
	v_pk_fma_f32 v[18:19], v[18:19], v[126:127], v[130:131]
	v_cvt_pk_bf16_f32 v16, v16, v17
	s_nop 0
	v_cvt_pk_bf16_f32 v17, v18, v19
	global_store_dwordx2 v[76:77], v[16:17], off offset:1536
	s_nop 0
	s_waitcnt vmcnt(10)
	v_pk_fma_f32 v[12:13], v[12:13], v[132:133], v[136:137]
	s_waitcnt vmcnt(10)
	v_pk_fma_f32 v[14:15], v[14:15], v[134:135], v[138:139]
	v_cvt_pk_bf16_f32 v12, v12, v13
	s_nop 0
	v_cvt_pk_bf16_f32 v13, v14, v15
	global_store_dwordx2 v[76:77], v[12:13], off offset:2048
	s_nop 0
	s_waitcnt vmcnt(9)
	v_pk_fma_f32 v[8:9], v[8:9], v[140:141], v[144:145]
	s_waitcnt vmcnt(9)
	v_pk_fma_f32 v[10:11], v[10:11], v[142:143], v[146:147]
	v_cvt_pk_bf16_f32 v8, v8, v9
	s_nop 0
	v_cvt_pk_bf16_f32 v9, v10, v11
	global_store_dwordx2 v[76:77], v[8:9], off offset:2560
	s_nop 0
	s_waitcnt vmcnt(8)
	v_pk_fma_f32 v[4:5], v[4:5], v[148:149], v[152:153]
	s_waitcnt vmcnt(8)
	v_pk_fma_f32 v[6:7], v[6:7], v[150:151], v[154:155]
	v_cvt_pk_bf16_f32 v4, v4, v5
	s_nop 0
	v_cvt_pk_bf16_f32 v5, v6, v7
	global_store_dwordx2 v[76:77], v[4:5], off offset:3072
	s_nop 0
	s_waitcnt vmcnt(7)
	v_pk_fma_f32 v[0:1], v[0:1], v[156:157], v[160:161]
	s_waitcnt vmcnt(7)
	v_pk_fma_f32 v[2:3], v[2:3], v[158:159], v[162:163]
	v_cvt_pk_bf16_f32 v0, v0, v1
	s_nop 0
	v_cvt_pk_bf16_f32 v1, v2, v3
	global_store_dwordx2 v[76:77], v[0:1], off offset:3584
	s_cbranch_scc1 .LBB0_1322

; __device__ __forceinline__ void ln_row(const float* in, float* out, bf16_t* outb, float* stat, const float* g, const float* bta, int lane) {
;     f32x4 v[8]; float s = 0.f;
; #pragma unroll
;     for (int j = 0; j < 8; ++j) { v[j] = *(const f32x4*)(in + 256 * j + 4 * lane); s += (v[j][0] + v[j][1]) + (v[j][2] + v[j][3]); }
;     const float mean = wave_sum(s) * (1.0f / 2048.0f); float s2 = 0.f;
; #pragma unroll
;     for (int j = 0; j < 8; ++j) { v[j] = v[j] - mean; s2 += (v[j][0] * v[j][0] + v[j][1] * v[j][1]) + (v[j][2] * v[j][2] + v[j][3] * v[j][3]); }
;     const float rstd = 1.0f / sqrtf(wave_sum(s2) * (1.0f / 2048.0f) + 1e-5f);
.LBB0_1558:
	global_load_dwordx4 v[28:31], v[52:53], off offset:-4096
	global_load_dwordx4 v[24:27], v[52:53], off offset:-3072
	global_load_dwordx4 v[20:23], v[52:53], off offset:-2048
	global_load_dwordx4 v[16:19], v[52:53], off offset:-1024
	global_load_dwordx4 v[12:15], v[52:53], off
	global_load_dwordx4 v[8:11], v[52:53], off offset:1024
	global_load_dwordx4 v[4:7], v[52:53], off offset:2048
	global_load_dwordx4 v[0:3], v[52:53], off offset:3072
	s_and_b64 vcc, exec, s[0:1]
	s_waitcnt vmcnt(7)
	v_mov_b32_e32 v62, v28
	s_waitcnt vmcnt(6) lgkmcnt(0)
	v_mov_b32_e32 v63, v24
	v_mov_b32_e32 v64, v29
	v_mov_b32_e32 v65, v25
	v_mov_b32_e32 v66, v30
	v_mov_b32_e32 v67, v26
	v_mov_b32_e32 v68, v31
	v_mov_b32_e32 v69, v27
	s_waitcnt vmcnt(5)
	v_mov_b32_e32 v70, v21
	v_mov_b32_e32 v71, v22
	v_mov_b32_e32 v72, v20
	v_mov_b32_e32 v73, v23
	v_pk_add_f32 v[62:63], v[62:63], v[64:65]
	v_pk_add_f32 v[64:65], v[66:67], v[68:69]
	v_pk_add_f32 v[66:67], v[70:71], v[72:73]
	v_pk_add_f32 v[62:63], v[62:63], v[64:65]
	v_pk_add_f32 v[64:65], v[66:67], v[66:67] op_sel:[0,1] op_sel_hi:[1,0]
	v_add_f32_e32 v62, 0, v62
	s_waitcnt vmcnt(4)
	v_add_f32_e32 v74, v16, v17
	v_add_f32_e32 v76, v18, v19
	s_waitcnt vmcnt(3)
	v_mov_b32_e32 v79, v12
	v_mov_b32_e32 v75, v14
	v_mov_b32_e32 v77, v15
	v_mov_b32_e32 v65, v13
	v_add_f32_e32 v78, v62, v63
	s_waitcnt vmcnt(2)
	v_mov_b32_e32 v80, v9
	v_mov_b32_e32 v81, v10
	v_mov_b32_e32 v82, v8
	v_mov_b32_e32 v83, v11
	v_pk_add_f32 v[68:69], v[74:75], v[76:77]
	v_pk_add_f32 v[62:63], v[78:79], v[64:65]
	v_pk_add_f32 v[70:71], v[80:81], v[82:83]
	v_pk_add_f32 v[62:63], v[62:63], v[68:69]
	v_pk_add_f32 v[66:67], v[70:71], v[70:71] op_sel:[0,1] op_sel_hi:[1,0]
	v_pk_add_f32 v[62:63], v[62:63], v[62:63] op_sel:[0,1] op_sel_hi:[1,0]
	s_waitcnt vmcnt(1)
	v_add_f32_e32 v84, v4, v5
	v_add_f32_e32 v86, v6, v7
	s_waitcnt vmcnt(0)
	v_mov_b32_e32 v85, v2
	v_mov_b32_e32 v87, v3
	v_mov_b32_e32 v67, v1
	v_mov_b32_e32 v63, v0
	v_pk_add_f32 v[72:73], v[84:85], v[86:87]
	v_pk_add_f32 v[62:63], v[62:63], v[66:67]
	s_nop 0
	v_pk_add_f32 v[62:63], v[62:63], v[72:73]
	s_nop 0
	v_add_f32_e32 v62, v62, v63
	ds_bpermute_b32 v63, v54, v62
	s_waitcnt lgkmcnt(0)
	v_add_f32_e32 v62, v62, v63
	ds_bpermute_b32 v63, v55, v62
	s_waitcnt lgkmcnt(0)
	v_add_f32_e32 v62, v62, v63
	ds_bpermute_b32 v63, v56, v62
	s_waitcnt lgkmcnt(0)
	v_add_f32_e32 v62, v62, v63
	ds_bpermute_b32 v63, v57, v62
	s_waitcnt lgkmcnt(0)
	v_add_f32_e32 v62, v62, v63
	ds_bpermute_b32 v63, v58, v62
	s_waitcnt lgkmcnt(0)
	v_add_f32_e32 v62, v62, v63
	ds_bpermute_b32 v63, v59, v62
	s_waitcnt lgkmcnt(0)
	v_add_f32_e32 v62, v62, v63
	v_fmamk_f32 v31, v62, 0xba000000, v31
	v_fmamk_f32 v29, v62, 0xba000000, v29
	v_fmamk_f32 v27, v62, 0xba000000, v27
	v_fmamk_f32 v25, v62, 0xba000000, v25
	v_fmamk_f32 v30, v62, 0xba000000, v30
	v_fmac_f32_e32 v28, 0xba000000, v62
	v_fmamk_f32 v26, v62, 0xba000000, v26
	v_fmac_f32_e32 v24, 0xba000000, v62
	v_fmamk_f32 v23, v62, 0xba000000, v23
	v_fmamk_f32 v22, v62, 0xba000000, v22
	v_fmamk_f32 v21, v62, 0xba000000, v21
	v_fmac_f32_e32 v20, 0xba000000, v62
	v_fmamk_f32 v19, v62, 0xba000000, v19
	v_fmamk_f32 v18, v62, 0xba000000, v18
	v_fmamk_f32 v17, v62, 0xba000000, v17
	v_fmac_f32_e32 v16, 0xba000000, v62
	v_fmamk_f32 v15, v62, 0xba000000, v15
	v_fmamk_f32 v14, v62, 0xba000000, v14
	v_fmamk_f32 v13, v62, 0xba000000, v13
	v_fmac_f32_e32 v12, 0xba000000, v62
	v_fmamk_f32 v11, v62, 0xba000000, v11
	v_fmamk_f32 v10, v62, 0xba000000, v10
	v_fmamk_f32 v9, v62, 0xba000000, v9
	v_fmac_f32_e32 v8, 0xba000000, v62
	v_fmamk_f32 v7, v62, 0xba000000, v7
	v_fmamk_f32 v6, v62, 0xba000000, v6
	v_fmamk_f32 v5, v62, 0xba000000, v5
	v_fmac_f32_e32 v4, 0xba000000, v62
	v_fmamk_f32 v3, v62, 0xba000000, v3
	v_fmamk_f32 v2, v62, 0xba000000, v2
	v_fmamk_f32 v1, v62, 0xba000000, v1
	v_fmac_f32_e32 v0, 0xba000000, v62
	v_mul_f32_e32 v62, v29, v29
	v_mul_f32_e32 v63, v31, v31
	v_mul_f32_e32 v64, v25, v25
	v_mul_f32_e32 v65, v27, v27
	v_mul_f32_e32 v66, v21, v21
	v_mul_f32_e32 v67, v23, v23
	v_fmac_f32_e32 v62, v28, v28
	v_fmac_f32_e32 v63, v30, v30
	v_fmac_f32_e32 v64, v24, v24
	v_fmac_f32_e32 v65, v26, v26
	v_mul_f32_e32 v68, v17, v17
	v_mul_f32_e32 v69, v19, v19
	v_fmac_f32_e32 v66, v20, v20
	v_fmac_f32_e32 v67, v22, v22
	v_add_f32_e32 v62, v62, v63
	v_add_f32_e32 v63, v64, v65
	v_mul_f32_e32 v70, v13, v13
	v_mul_f32_e32 v71, v15, v15
	v_fmac_f32_e32 v68, v16, v16
	v_fmac_f32_e32 v69, v18, v18
	v_add_f32_e32 v64, v66, v67
	v_add_f32_e32 v62, v62, v63
	v_mul_f32_e32 v72, v9, v9
	v_mul_f32_e32 v73, v11, v11
	v_fmac_f32_e32 v70, v12, v12
	v_fmac_f32_e32 v71, v14, v14
	v_add_f32_e32 v65, v68, v69
	v_add_f32_e32 v62, v64, v62
	v_mul_f32_e32 v74, v5, v5
	v_mul_f32_e32 v75, v7, v7
	v_fmac_f32_e32 v72, v8, v8
	v_fmac_f32_e32 v73, v10, v10
	v_add_f32_e32 v66, v70, v71
	v_add_f32_e32 v62, v65, v62
	v_fmac_f32_e32 v74, v4, v4
	v_fmac_f32_e32 v75, v6, v6
	v_add_f32_e32 v67, v72, v73
	v_add_f32_e32 v62, v66, v62
	v_mul_f32_e32 v63, v1, v1
	v_mul_f32_e32 v64, v3, v3
	v_add_f32_e32 v68, v74, v75
	v_add_f32_e32 v62, v67, v62
	v_fmac_f32_e32 v63, v0, v0
	v_fmac_f32_e32 v64, v2, v2
	v_add_f32_e32 v62, v68, v62
	v_add_f32_e32 v63, v63, v64
	v_add_f32_e32 v62, v63, v62
	ds_bpermute_b32 v63, v54, v62
	s_waitcnt lgkmcnt(0)
	v_add_f32_e32 v62, v62, v63
	ds_bpermute_b32 v63, v55, v62
	s_waitcnt lgkmcnt(0)
	v_add_f32_e32 v62, v62, v63
	ds_bpermute_b32 v63, v56, v62
	s_waitcnt lgkmcnt(0)
	v_add_f32_e32 v62, v62, v63
	ds_bpermute_b32 v63, v57, v62
	s_waitcnt lgkmcnt(0)
	v_add_f32_e32 v62, v62, v63
	ds_bpermute_b32 v63, v58, v62
	s_waitcnt lgkmcnt(0)
	v_add_f32_e32 v62, v62, v63
	ds_bpermute_b32 v63, v59, v62
	s_cbranch_vccnz .LBB0_1557
; __device__ __forceinline__ unsigned cvt_pk_bf16(float lo, float hi) { unsigned r; asm volatile("v_cvt_pk_bf16_f32 %0, %1, %2" : "=v"(r) : "v"(lo), "v"(hi)); return r; }
; __device__ __forceinline__ void ln_row(const float* in, float* out, bf16_t* outb, float* stat, const float* g, const float* bta, int lane) {
;     ...
;     const float rstd = 1.0f / sqrtf(wave_sum(s2) * (1.0f / 2048.0f) + 1e-5f);
;     if (stat && lane == 0) *(f32x2v*)stat = (f32x2v){mean, rstd};
; #pragma unroll
;     for (int j = 0; j < 8; ++j) {
;         const f32x4 gg = *(const f32x4*)(g + 256 * j + 4 * lane), bb = *(const f32x4*)(bta + 256 * j + 4 * lane);
;         const f32x4 y = v[j] * rstd * gg + bb;
;         if (out) *(f32x4*)(out + 256 * j + 4 * lane) = y;
;         if (outb) { u32x2 w; w.x = cvt_pk_bf16(y[0], y[1]); w.y = cvt_pk_bf16(y[2], y[3]); *(u32x2*)(outb + 256 * j + 4 * lane) = w; }
;     }
	global_load_dwordx4 v[100:103], v[32:33], off
	global_load_dwordx4 v[104:107], v[34:35], off
	global_load_dwordx4 v[108:111], v[32:33], off offset:1024
	global_load_dwordx4 v[112:115], v[34:35], off offset:1024
	global_load_dwordx4 v[116:119], v[32:33], off offset:2048
	global_load_dwordx4 v[120:123], v[34:35], off offset:2048
	global_load_dwordx4 v[124:127], v[32:33], off offset:3072
	global_load_dwordx4 v[128:131], v[34:35], off offset:3072
	global_load_dwordx4 v[132:135], v[36:37], off
	global_load_dwordx4 v[136:139], v[38:39], off
	global_load_dwordx4 v[140:143], v[40:41], off
	global_load_dwordx4 v[144:147], v[42:43], off
	global_load_dwordx4 v[148:151], v[44:45], off
	global_load_dwordx4 v[152:155], v[46:47], off
	global_load_dwordx4 v[156:159], v[48:49], off
	global_load_dwordx4 v[160:163], v[50:51], off
	s_waitcnt lgkmcnt(0)
	v_add_f32_e32 v62, v62, v63
	v_fmamk_f32 v62, v62, 0x3a000000, v60
	v_mul_f32_e32 v63, 0x4f800000, v62
	v_cmp_gt_f32_e32 vcc, s5, v62
	s_nop 1
	v_cndmask_b32_e32 v62, v62, v63, vcc
	v_sqrt_f32_e32 v63, v62
	s_nop 0
	v_add_u32_e32 v72, -1, v63
	v_add_u32_e32 v73, 1, v63
	v_fma_f32 v74, -v72, v63, v62
	v_fma_f32 v75, -v73, v63, v62
	v_cmp_ge_f32_e64 s[2:3], 0, v74
	s_nop 1
	v_cndmask_b32_e64 v63, v63, v72, s[2:3]
	v_cmp_lt_f32_e64 s[2:3], 0, v75
	s_nop 1
	v_cndmask_b32_e64 v63, v63, v73, s[2:3]
	v_mul_f32_e32 v72, 0x37800000, v63
	v_cndmask_b32_e32 v63, v63, v72, vcc
	v_cmp_class_f32_e32 vcc, v62, v61
	s_nop 1
	v_cndmask_b32_e32 v62, v63, v62, vcc
	v_div_scale_f32 v63, s[2:3], v62, v62, 1.0
	v_rcp_f32_e32 v72, v63
	v_div_scale_f32 v73, vcc, 1.0, v62, 1.0
	v_fma_f32 v74, -v63, v72, 1.0
	v_fmac_f32_e32 v72, v74, v72
	v_mul_f32_e32 v74, v73, v72
	v_fma_f32 v75, -v63, v74, v73
	v_fmac_f32_e32 v74, v75, v72
	v_fma_f32 v63, -v63, v74, v73
	v_div_fmas_f32 v63, v63, v72, v74
	v_div_fixup_f32 v72, v63, v62, 1.0
	v_pk_mul_f32 v[28:29], v[28:29], v[72:73] op_sel_hi:[1,0]
	v_pk_mul_f32 v[30:31], v[30:31], v[72:73] op_sel_hi:[1,0]
	v_pk_mul_f32 v[26:27], v[26:27], v[72:73] op_sel_hi:[1,0]
	v_pk_mul_f32 v[24:25], v[24:25], v[72:73] op_sel_hi:[1,0]
	v_pk_mul_f32 v[22:23], v[22:23], v[72:73] op_sel_hi:[1,0]
	v_pk_mul_f32 v[20:21], v[20:21], v[72:73] op_sel_hi:[1,0]
	v_pk_mul_f32 v[18:19], v[18:19], v[72:73] op_sel_hi:[1,0]
	v_pk_mul_f32 v[16:17], v[16:17], v[72:73] op_sel_hi:[1,0]
	v_pk_mul_f32 v[14:15], v[14:15], v[72:73] op_sel_hi:[1,0]
	v_pk_mul_f32 v[12:13], v[12:13], v[72:73] op_sel_hi:[1,0]
	v_pk_mul_f32 v[10:11], v[10:11], v[72:73] op_sel_hi:[1,0]
	v_pk_mul_f32 v[8:9], v[8:9], v[72:73] op_sel_hi:[1,0]
	v_pk_mul_f32 v[6:7], v[6:7], v[72:73] op_sel_hi:[1,0]
	v_pk_mul_f32 v[4:5], v[4:5], v[72:73] op_sel_hi:[1,0]
	v_pk_mul_f32 v[2:3], v[2:3], v[72:73] op_sel_hi:[1,0]
	v_pk_mul_f32 v[0:1], v[0:1], v[72:73] op_sel_hi:[1,0]
	s_waitcnt vmcnt(14)
	v_pk_fma_f32 v[30:31], v[30:31], v[102:103], v[106:107]
	s_waitcnt vmcnt(14)
	v_pk_fma_f32 v[28:29], v[28:29], v[100:101], v[104:105]
	global_store_dwordx4 v[52:53], v[28:31], off offset:-4096
	s_nop 0
	s_waitcnt vmcnt(13)
	v_pk_fma_f32 v[24:25], v[24:25], v[108:109], v[112:113]
	s_waitcnt vmcnt(13)
	v_pk_fma_f32 v[26:27], v[26:27], v[110:111], v[114:115]
	global_store_dwordx4 v[52:53], v[24:27], off offset:-3072
	s_nop 0
	s_waitcnt vmcnt(12)
	v_pk_fma_f32 v[20:21], v[20:21], v[116:117], v[120:121]
	s_waitcnt vmcnt(12)
	v_pk_fma_f32 v[22:23], v[22:23], v[118:119], v[122:123]
	global_store_dwordx4 v[52:53], v[20:23], off offset:-2048
	s_nop 0
	s_waitcnt vmcnt(11)
	v_pk_fma_f32 v[16:17], v[16:17], v[124:125], v[128:129]
	s_waitcnt vmcnt(11)
	v_pk_fma_f32 v[18:19], v[18:19], v[126:127], v[130:131]
	global_store_dwordx4 v[52:53], v[16:19], off offset:-1024
	s_nop 0
	s_waitcnt vmcnt(10)
	v_pk_fma_f32 v[12:13], v[12:13], v[132:133], v[136:137]
	s_waitcnt vmcnt(10)
	v_pk_fma_f32 v[14:15], v[14:15], v[134:135], v[138:139]
	global_store_dwordx4 v[52:53], v[12:15], off
	s_nop 0
	s_waitcnt vmcnt(9)
	v_pk_fma_f32 v[8:9], v[8:9], v[140:141], v[144:145]
	s_waitcnt vmcnt(9)
	v_pk_fma_f32 v[10:11], v[10:11], v[142:143], v[146:147]
	global_store_dwordx4 v[52:53], v[8:11], off offset:1024
	s_nop 0
	s_waitcnt vmcnt(8)
	v_pk_fma_f32 v[4:5], v[4:5], v[148:149], v[152:153]
	s_waitcnt vmcnt(8)
	v_pk_fma_f32 v[6:7], v[6:7], v[150:151], v[154:155]
	global_store_dwordx4 v[52:53], v[4:7], off offset:2048
	s_nop 0
	s_waitcnt vmcnt(7)
	v_pk_fma_f32 v[0:1], v[0:1], v[156:157], v[160:161]
	s_waitcnt vmcnt(7)
	v_pk_fma_f32 v[2:3], v[2:3], v[158:159], v[162:163]
	global_store_dwordx4 v[52:53], v[0:3], off offset:3072
	s_branch .LBB0_1557
